# v73 + first grid barrier census loop issues its 16 counter loads back to back (one wait) instead of one at a time
# baseline (speedup 1.0000x reference)
.LBB0_29:
	s_mov_b64 s[36:37], -1
	s_mov_b64 s[38:39], -1
	s_waitcnt lgkmcnt(0)
	v_readlane_b32 s2, v250, 55
	v_readlane_b32 s3, v250, 56
	s_nop 4
	global_load_dword v8, v2, s[2:3] sc1
	v_readlane_b32 s2, v250, 57
	v_readlane_b32 s3, v250, 58
	s_nop 4
	global_load_dword v9, v2, s[2:3] sc1
	v_readlane_b32 s2, v250, 59
	v_readlane_b32 s3, v250, 60
	s_nop 4
	global_load_dword v11, v2, s[2:3] sc1
	v_readlane_b32 s2, v250, 61
	v_readlane_b32 s3, v250, 62
	s_nop 4
	global_load_dword v12, v2, s[2:3] sc1
	v_readlane_b32 s2, v250, 63
	v_readlane_b32 s3, v251, 0
	s_nop 4
	global_load_dword v13, v2, s[2:3] sc1
	v_readlane_b32 s2, v251, 1
	v_readlane_b32 s3, v251, 2
	s_nop 4
	global_load_dword v14, v2, s[2:3] sc1
	v_readlane_b32 s2, v251, 3
	v_readlane_b32 s3, v251, 4
	s_nop 4
	global_load_dword v15, v2, s[2:3] sc1
	v_readlane_b32 s2, v251, 5
	v_readlane_b32 s3, v251, 6
	s_nop 4
	global_load_dword v16, v2, s[2:3] sc1
	v_readlane_b32 s2, v251, 7
	v_readlane_b32 s3, v251, 8
	s_nop 4
	global_load_dword v3, v2, s[2:3] sc1
	v_readlane_b32 s2, v251, 9
	v_readlane_b32 s3, v251, 10
	s_nop 4
	global_load_dword v0, v2, s[2:3] sc1
	v_readlane_b32 s2, v251, 11
	v_readlane_b32 s3, v251, 12
	s_nop 4
	global_load_dword v5, v2, s[2:3] sc1
	v_readlane_b32 s2, v251, 13
	v_readlane_b32 s3, v251, 14
	s_nop 4
	global_load_dword v1, v2, s[2:3] sc1
	v_readlane_b32 s2, v251, 15
	v_readlane_b32 s3, v251, 16
	s_nop 4
	global_load_dword v6, v2, s[2:3] sc1
	v_readlane_b32 s2, v251, 17
	v_readlane_b32 s3, v251, 18
	s_nop 4
	global_load_dword v4, v2, s[2:3] sc1
	v_readlane_b32 s2, v251, 19
	v_readlane_b32 s3, v251, 20
	s_nop 4
	global_load_dword v10, v2, s[2:3] sc1
	v_readlane_b32 s2, v251, 21
	v_readlane_b32 s3, v251, 22
	s_nop 4
	global_load_dword v7, v2, s[2:3] sc1
	s_waitcnt vmcnt(0)
	v_add_u32_e32 v17, v9, v8
	v_add_u32_e32 v17, v17, v11
	v_add_u32_e32 v17, v17, v12
	v_add_u32_e32 v17, v17, v13
	v_add_u32_e32 v17, v17, v14
	v_add_u32_e32 v17, v17, v15
	v_add_u32_e32 v17, v17, v16
	v_add_u32_e32 v18, v3, v17
	v_add_u32_e32 v18, v18, v0
	v_add_u32_e32 v18, v18, v5
	v_add_u32_e32 v18, v18, v1
	v_add_u32_e32 v18, v18, v6
	v_add_u32_e32 v18, v18, v4
	v_add_u32_e32 v18, v18, v10
	v_add_u32_e32 v18, v18, v7
	v_readlane_b32 s2, v252, 25
	s_nop 1
	v_cmp_eq_u32_e32 vcc, s2, v18
	s_cbranch_vccnz .LBB0_28
	s_and_b32 s2, s20, 0xff
	s_cmp_eq_u32 s2, 0
	s_mov_b64 s[40:41], -1
	s_sleep 1
	s_cbranch_scc0 .LBB0_33
	global_load_dword v18, v2, s[0:1] sc1
	s_waitcnt vmcnt(0)
	v_cmp_eq_u32_e32 vcc, 0, v18
	s_cbranch_vccnz .LBB0_35
	s_mov_b64 s[40:41], 0
